# fused-LN per-panel arrival counters spread over 8 cache lines (8 per line) instead of 2
# speedup vs baseline: 1.0068x; 1.0034x over previous
.LBB0_80:
	s_or_b64 exec, exec, s[4:5]
	s_waitcnt vmcnt(0)
	s_barrier
	s_and_saveexec_b64 s[4:5], s[18:19]
	s_cbranch_execz .LBB0_85
	s_mov_b64 s[10:11], exec
	s_and_b32 s7, s6, 7
	s_lshl_b32 s7, s7, 7
	s_lshr_b32 s8, s6, 3
	s_lshl_b32 s8, s8, 2
	s_add_i32 s8, s8, s7
	s_sub_i32 s8, s8, 0xc0
	s_ashr_i32 s9, s8, 31
	v_readlane_b32 s7, v250, 12
	v_mbcnt_lo_u32_b32 v48, s10, 0
	s_add_u32 s8, s7, s8
	v_readlane_b32 s7, v250, 13
	v_mbcnt_hi_u32_b32 v48, s11, v48
	s_addc_u32 s9, s7, s9
	v_cmp_eq_u32_e32 vcc, 0, v48
	s_and_saveexec_b64 s[12:13], vcc
	s_cbranch_execz .LBB0_83
	s_bcnt1_i32_b64 s7, s[10:11]
	v_mov_b32_e32 v48, s7
	global_atomic_add v145, v48, s[8:9]

.LBB0_440:
	s_or_b64 exec, exec, s[4:5]
	s_waitcnt vmcnt(0)
	s_barrier
	s_and_saveexec_b64 s[4:5], s[0:1]
	s_cbranch_execz .LBB0_445
	s_mov_b64 s[14:15], exec
	s_and_b32 s13, s12, 7
	s_lshl_b32 s13, s13, 7
	s_lshr_b32 s6, s12, 3
	s_lshl_b32 s6, s6, 2
	s_add_i32 s6, s6, s13
	s_sub_i32 s6, s6, 0xc0
	s_ashr_i32 s7, s6, 31
	v_readlane_b32 s13, v250, 12
	v_mbcnt_lo_u32_b32 v0, s14, 0
	s_add_u32 s6, s13, s6
	v_readlane_b32 s13, v250, 13
	v_mbcnt_hi_u32_b32 v0, s15, v0
	s_addc_u32 s7, s13, s7
	v_cmp_eq_u32_e32 vcc, 0, v0
	s_and_saveexec_b64 s[16:17], vcc
	s_cbranch_execz .LBB0_443
	s_bcnt1_i32_b64 s13, s[14:15]
	v_mov_b32_e32 v0, s13
	global_atomic_add v145, v0, s[6:7]
